# combined version with the G1 epilogue transposition software-pipelined one store group ahead
# speedup vs baseline: 1.0093x; 1.0013x over previous
; __device__ __forceinline__ unsigned cvt_pk_bf16(float lo, float hi) { unsigned r; asm volatile("v_cvt_pk_bf16_f32 %0, %1, %2" : "=v"(r) : "v"(lo), "v"(hi)); return r; }
;   DI void operator()(const pg8::f32x4 (&acc)[2][2][4][2], const pg8::Unit& u, int wr, int wc, int fr, int fq) const {
;     const int row0 = u.pm * 256 + wr * 64 + fr, col0 = u.pn * 256 + wc * 32 + 8 * fq;
; #pragma unroll
;     for (int ai = 0; ai < 2; ++ai)
; #pragma unroll
;       for (int m = 0; m < 4; ++m) {
;         bfr* rowp = P + (size_t)(row0 + ai * 128 + m * 16) * PW;
; #pragma unroll
;         for (int bj = 0; bj < 2; ++bj) {
;           const int col = col0 + bj * 128;
;           if (col < PW) {
;             pg8::f32x4 v0 = acc[ai][bj][m][0], v1 = acc[ai][bj][m][1];
;             u32x4 w; w.x = pg8::cvt_pk_bf16(v0[0], v0[1]); w.y = pg8::cvt_pk_bf16(v0[2], v0[3]); w.z = pg8::cvt_pk_bf16(v1[0], v1[1]); w.w = pg8::cvt_pk_bf16(v1[2], v1[3]);
;             *(u32x4*)(rowp + col) = w;
;           }
;         }
;       }
;   }
.LBB0_223:
	v_and_b32_e32 v232, 63, v182
	v_lshrrev_b32_e32 v233, 2, v232
	v_and_b32_e32 v234, 3, v232
	v_lshl_add_u32 v235, v234, 4, v233
	v_lshlrev_b32_e32 v235, 2, v235
	v_and_b32_e32 v236, 0xfffffff0, v142
	v_add_u32_e32 v236, v236, v233
	v_lshl_add_u32 v236, s34, 8, v236
	v_and_b32_e32 v237, 0xffffffe0, v144
	v_lshl_add_u32 v237, v234, 3, v237
	v_lshl_or_b32 v237, s31, 8, v237
	s_movk_i32 s4, 0xcc0
	v_cmp_gt_i32_e32 vcc, s4, v237
	v_or_b32_e32 v238, 0x80, v237
	v_cmp_gt_i32_e64 s[4:5], s4, v238
	s_mov_b64 s[18:19], exec
	v_mov_b32_e32 v239, v235
	v_cvt_pk_bf16_f32 v240, v124, v125
	v_cvt_pk_bf16_f32 v241, v126, v127
	v_cvt_pk_bf16_f32 v242, v120, v121
	v_cvt_pk_bf16_f32 v243, v122, v123
	ds_bpermute_b32 v244, v239, v240
	ds_bpermute_b32 v245, v239, v241
	ds_bpermute_b32 v246, v239, v242
	ds_bpermute_b32 v247, v239, v243
	v_cvt_pk_bf16_f32 v240, v116, v117
	v_cvt_pk_bf16_f32 v241, v118, v119
	v_cvt_pk_bf16_f32 v242, v108, v109
	v_cvt_pk_bf16_f32 v243, v110, v111
	ds_bpermute_b32 v232, v239, v240
	ds_bpermute_b32 v233, v239, v241
	ds_bpermute_b32 v234, v239, v242
	ds_bpermute_b32 v235, v239, v243
	s_waitcnt lgkmcnt(4)
	v_add_u32_e32 v238, 0, v236
	v_mov_b64_e32 v[248:249], s[84:85]
	v_mad_i64_i32 v[248:249], s[98:99], v238, s88, v[248:249]
	v_ashrrev_i32_e32 v251, 31, v237
	v_mov_b32_e32 v250, v237
	v_lshl_add_u64 v[248:249], v[250:251], 1, v[248:249]
	s_and_b64 exec, s[18:19], vcc
	global_store_dwordx4 v[248:249], v[244:247], off
	s_mov_b64 exec, s[18:19]
	v_cvt_pk_bf16_f32 v240, v112, v113
	v_cvt_pk_bf16_f32 v241, v114, v115
	v_cvt_pk_bf16_f32 v242, v104, v105
	v_cvt_pk_bf16_f32 v243, v106, v107
	ds_bpermute_b32 v244, v239, v240
	ds_bpermute_b32 v245, v239, v241
	ds_bpermute_b32 v246, v239, v242
	ds_bpermute_b32 v247, v239, v243
	s_waitcnt lgkmcnt(4)
	s_and_b64 exec, s[18:19], s[4:5]
	global_store_dwordx4 v[248:249], v[232:235], off offset:256
	s_mov_b64 exec, s[18:19]
	v_cvt_pk_bf16_f32 v240, v100, v101
	v_cvt_pk_bf16_f32 v241, v102, v103
	v_cvt_pk_bf16_f32 v242, v92, v93
	v_cvt_pk_bf16_f32 v243, v94, v95
	ds_bpermute_b32 v232, v239, v240
	ds_bpermute_b32 v233, v239, v241
	ds_bpermute_b32 v234, v239, v242
	ds_bpermute_b32 v235, v239, v243
	s_waitcnt lgkmcnt(4)
	v_add_u32_e32 v238, 16, v236
	v_mov_b64_e32 v[248:249], s[84:85]
	v_mad_i64_i32 v[248:249], s[98:99], v238, s88, v[248:249]
	v_ashrrev_i32_e32 v251, 31, v237
	v_mov_b32_e32 v250, v237
	v_lshl_add_u64 v[248:249], v[250:251], 1, v[248:249]
	s_and_b64 exec, s[18:19], vcc
	global_store_dwordx4 v[248:249], v[244:247], off
	s_mov_b64 exec, s[18:19]
	v_cvt_pk_bf16_f32 v240, v96, v97
	v_cvt_pk_bf16_f32 v241, v98, v99
	v_cvt_pk_bf16_f32 v242, v88, v89
	v_cvt_pk_bf16_f32 v243, v90, v91
	ds_bpermute_b32 v244, v239, v240
	ds_bpermute_b32 v245, v239, v241
	ds_bpermute_b32 v246, v239, v242
	ds_bpermute_b32 v247, v239, v243
	s_waitcnt lgkmcnt(4)
	s_and_b64 exec, s[18:19], s[4:5]
	global_store_dwordx4 v[248:249], v[232:235], off offset:256
	s_mov_b64 exec, s[18:19]
	v_cvt_pk_bf16_f32 v240, v84, v85
	v_cvt_pk_bf16_f32 v241, v86, v87
	v_cvt_pk_bf16_f32 v242, v76, v77
	v_cvt_pk_bf16_f32 v243, v78, v79
	ds_bpermute_b32 v232, v239, v240
	ds_bpermute_b32 v233, v239, v241
	ds_bpermute_b32 v234, v239, v242
	ds_bpermute_b32 v235, v239, v243
	s_waitcnt lgkmcnt(4)
	v_add_u32_e32 v238, 32, v236
	v_mov_b64_e32 v[248:249], s[84:85]
	v_mad_i64_i32 v[248:249], s[98:99], v238, s88, v[248:249]
	v_ashrrev_i32_e32 v251, 31, v237
	v_mov_b32_e32 v250, v237
	v_lshl_add_u64 v[248:249], v[250:251], 1, v[248:249]
	s_and_b64 exec, s[18:19], vcc
	global_store_dwordx4 v[248:249], v[244:247], off
	s_mov_b64 exec, s[18:19]
	v_cvt_pk_bf16_f32 v240, v80, v81
	v_cvt_pk_bf16_f32 v241, v82, v83
	v_cvt_pk_bf16_f32 v242, v72, v73
	v_cvt_pk_bf16_f32 v243, v74, v75
	ds_bpermute_b32 v244, v239, v240
	ds_bpermute_b32 v245, v239, v241
	ds_bpermute_b32 v246, v239, v242
	ds_bpermute_b32 v247, v239, v243
	s_waitcnt lgkmcnt(4)
	s_and_b64 exec, s[18:19], s[4:5]
	global_store_dwordx4 v[248:249], v[232:235], off offset:256
	s_mov_b64 exec, s[18:19]
	v_cvt_pk_bf16_f32 v240, v68, v69
	v_cvt_pk_bf16_f32 v241, v70, v71
	v_cvt_pk_bf16_f32 v242, v64, v65
	v_cvt_pk_bf16_f32 v243, v66, v67
	ds_bpermute_b32 v232, v239, v240
	ds_bpermute_b32 v233, v239, v241
	ds_bpermute_b32 v234, v239, v242
	ds_bpermute_b32 v235, v239, v243
	s_waitcnt lgkmcnt(4)
; __device__ __forceinline__ unsigned cvt_pk_bf16(float lo, float hi) { unsigned r; asm volatile("v_cvt_pk_bf16_f32 %0, %1, %2" : "=v"(r) : "v"(lo), "v"(hi)); return r; }
;   DI void operator()(const pg8::f32x4 (&acc)[2][2][4][2], const pg8::Unit& u, int wr, int wc, int fr, int fq) const {
;     const int row0 = u.pm * 256 + wr * 64 + fr, col0 = u.pn * 256 + wc * 32 + 8 * fq;
; #pragma unroll
;     for (int ai = 0; ai < 2; ++ai)
; #pragma unroll
;       for (int m = 0; m < 4; ++m) {
;         bfr* rowp = P + (size_t)(row0 + ai * 128 + m * 16) * PW;
; #pragma unroll
;         for (int bj = 0; bj < 2; ++bj) {
;           const int col = col0 + bj * 128;
;           if (col < PW) {
;             pg8::f32x4 v0 = acc[ai][bj][m][0], v1 = acc[ai][bj][m][1];
;             u32x4 w; w.x = pg8::cvt_pk_bf16(v0[0], v0[1]); w.y = pg8::cvt_pk_bf16(v0[2], v0[3]); w.z = pg8::cvt_pk_bf16(v1[0], v1[1]); w.w = pg8::cvt_pk_bf16(v1[2], v1[3]);
;             *(u32x4*)(rowp + col) = w;
;           }
;         }
;       }
;   }
	v_add_u32_e32 v238, 48, v236
	v_mov_b64_e32 v[248:249], s[84:85]
	v_mad_i64_i32 v[248:249], s[98:99], v238, s88, v[248:249]
	v_ashrrev_i32_e32 v251, 31, v237
	v_mov_b32_e32 v250, v237
	v_lshl_add_u64 v[248:249], v[250:251], 1, v[248:249]
	s_and_b64 exec, s[18:19], vcc
	global_store_dwordx4 v[248:249], v[244:247], off
	s_mov_b64 exec, s[18:19]
	v_cvt_pk_bf16_f32 v240, v60, v61
	v_cvt_pk_bf16_f32 v241, v62, v63
	v_cvt_pk_bf16_f32 v242, v56, v57
	v_cvt_pk_bf16_f32 v243, v58, v59
	ds_bpermute_b32 v244, v239, v240
	ds_bpermute_b32 v245, v239, v241
	ds_bpermute_b32 v246, v239, v242
	ds_bpermute_b32 v247, v239, v243
	s_waitcnt lgkmcnt(4)
	s_and_b64 exec, s[18:19], s[4:5]
	global_store_dwordx4 v[248:249], v[232:235], off offset:256
	s_mov_b64 exec, s[18:19]
	v_cvt_pk_bf16_f32 v240, v52, v53
	v_cvt_pk_bf16_f32 v241, v54, v55
	v_cvt_pk_bf16_f32 v242, v44, v45
	v_cvt_pk_bf16_f32 v243, v46, v47
	ds_bpermute_b32 v232, v239, v240
	ds_bpermute_b32 v233, v239, v241
	ds_bpermute_b32 v234, v239, v242
	ds_bpermute_b32 v235, v239, v243
	s_waitcnt lgkmcnt(4)
	v_add_u32_e32 v238, 128, v236
	v_mov_b64_e32 v[248:249], s[84:85]
	v_mad_i64_i32 v[248:249], s[98:99], v238, s88, v[248:249]
	v_ashrrev_i32_e32 v251, 31, v237
	v_mov_b32_e32 v250, v237
	v_lshl_add_u64 v[248:249], v[250:251], 1, v[248:249]
	s_and_b64 exec, s[18:19], vcc
	global_store_dwordx4 v[248:249], v[244:247], off
	s_mov_b64 exec, s[18:19]
	v_cvt_pk_bf16_f32 v240, v48, v49
	v_cvt_pk_bf16_f32 v241, v50, v51
	v_cvt_pk_bf16_f32 v242, v40, v41
	v_cvt_pk_bf16_f32 v243, v42, v43
	ds_bpermute_b32 v244, v239, v240
	ds_bpermute_b32 v245, v239, v241
	ds_bpermute_b32 v246, v239, v242
	ds_bpermute_b32 v247, v239, v243
	s_waitcnt lgkmcnt(4)
	s_and_b64 exec, s[18:19], s[4:5]
	global_store_dwordx4 v[248:249], v[232:235], off offset:256
	s_mov_b64 exec, s[18:19]
	v_cvt_pk_bf16_f32 v240, v36, v37
	v_cvt_pk_bf16_f32 v241, v38, v39
	v_cvt_pk_bf16_f32 v242, v28, v29
	v_cvt_pk_bf16_f32 v243, v30, v31
	ds_bpermute_b32 v232, v239, v240
	ds_bpermute_b32 v233, v239, v241
	ds_bpermute_b32 v234, v239, v242
	ds_bpermute_b32 v235, v239, v243
	s_waitcnt lgkmcnt(4)
	v_add_u32_e32 v238, 144, v236
	v_mov_b64_e32 v[248:249], s[84:85]
	v_mad_i64_i32 v[248:249], s[98:99], v238, s88, v[248:249]
	v_ashrrev_i32_e32 v251, 31, v237
	v_mov_b32_e32 v250, v237
	v_lshl_add_u64 v[248:249], v[250:251], 1, v[248:249]
	s_and_b64 exec, s[18:19], vcc
	global_store_dwordx4 v[248:249], v[244:247], off
	s_mov_b64 exec, s[18:19]
	v_cvt_pk_bf16_f32 v240, v32, v33
	v_cvt_pk_bf16_f32 v241, v34, v35
	v_cvt_pk_bf16_f32 v242, v24, v25
	v_cvt_pk_bf16_f32 v243, v26, v27
	ds_bpermute_b32 v244, v239, v240
	ds_bpermute_b32 v245, v239, v241
	ds_bpermute_b32 v246, v239, v242
	ds_bpermute_b32 v247, v239, v243
	s_waitcnt lgkmcnt(4)
	s_and_b64 exec, s[18:19], s[4:5]
	global_store_dwordx4 v[248:249], v[232:235], off offset:256
	s_mov_b64 exec, s[18:19]
	v_cvt_pk_bf16_f32 v240, v20, v21
	v_cvt_pk_bf16_f32 v241, v22, v23
	v_cvt_pk_bf16_f32 v242, v12, v13
	v_cvt_pk_bf16_f32 v243, v14, v15
	ds_bpermute_b32 v232, v239, v240
	ds_bpermute_b32 v233, v239, v241
	ds_bpermute_b32 v234, v239, v242
	ds_bpermute_b32 v235, v239, v243
	s_waitcnt lgkmcnt(4)
	v_add_u32_e32 v238, 160, v236
	v_mov_b64_e32 v[248:249], s[84:85]
	v_mad_i64_i32 v[248:249], s[98:99], v238, s88, v[248:249]
	v_ashrrev_i32_e32 v251, 31, v237
	v_mov_b32_e32 v250, v237
	v_lshl_add_u64 v[248:249], v[250:251], 1, v[248:249]
	s_and_b64 exec, s[18:19], vcc
	global_store_dwordx4 v[248:249], v[244:247], off
	s_mov_b64 exec, s[18:19]
	v_cvt_pk_bf16_f32 v240, v16, v17
	v_cvt_pk_bf16_f32 v241, v18, v19
	v_cvt_pk_bf16_f32 v242, v8, v9
	v_cvt_pk_bf16_f32 v243, v10, v11
	ds_bpermute_b32 v244, v239, v240
	ds_bpermute_b32 v245, v239, v241
	ds_bpermute_b32 v246, v239, v242
	ds_bpermute_b32 v247, v239, v243
	s_waitcnt lgkmcnt(4)
	s_and_b64 exec, s[18:19], s[4:5]
	global_store_dwordx4 v[248:249], v[232:235], off offset:256
	s_mov_b64 exec, s[18:19]
	v_cvt_pk_bf16_f32 v240, v4, v5
	v_cvt_pk_bf16_f32 v241, v6, v7
	v_cvt_pk_bf16_f32 v242, v0, v1
	v_cvt_pk_bf16_f32 v243, v2, v3
	ds_bpermute_b32 v232, v239, v240
	ds_bpermute_b32 v233, v239, v241
	ds_bpermute_b32 v234, v239, v242
	ds_bpermute_b32 v235, v239, v243
	s_waitcnt lgkmcnt(4)
	v_add_u32_e32 v238, 176, v236
	v_mov_b64_e32 v[248:249], s[84:85]
	v_mad_i64_i32 v[248:249], s[98:99], v238, s88, v[248:249]
	v_ashrrev_i32_e32 v251, 31, v237
	v_mov_b32_e32 v250, v237
	v_lshl_add_u64 v[248:249], v[250:251], 1, v[248:249]
	s_and_b64 exec, s[18:19], vcc
	global_store_dwordx4 v[248:249], v[244:247], off
	s_mov_b64 exec, s[18:19]
	s_waitcnt lgkmcnt(0)
	s_and_b64 exec, s[18:19], s[4:5]
	global_store_dwordx4 v[248:249], v[232:235], off offset:256
	s_mov_b64 exec, s[18:19]
	s_andn2_b64 vcc, exec, s[2:3]
	s_mov_b64 s[2:3], -1
	s_cbranch_vccnz .LBB0_216
